# GEMM per-unit accumulator zeroing: 127 v_mov_b32 replaced by 1 v_mov_b32 + 63 v_mov_b64 (on top of v32)
# baseline (speedup 1.0000x reference)
; template <class Epi, class Sched, bool ALIGN_EPI = false, bool SP2 = false>
; __device__ __forceinline__ void gemm_phase(PG8_LAS unsigned char* lds, const Gemm g, const Sched& S, const Epi& E) {
;     ...
;         const bool has_next = S.next(ui + 1, nxt);
;         const char* nA = has_next ? (const char*)g.A + (size_t)nxt.pm * tstep : cA; const char* nB = has_next ? (const char*)g.Bt + (size_t)nxt.pn * tstep : cB;
;     ...
;         for (int a = 0; a < 2; ++a)
; #pragma unroll
;             for (int b = 0; b < 2; ++b)
; #pragma unroll
;                 for (int m = 0; m < 4; ++m)
; #pragma unroll
;                     for (int n = 0; n < 2; ++n) acc[a][b][m][n] = (f32x4){0.f, 0.f, 0.f, 0.f};
.LBB0_118:
	s_ashr_i32 s35, s34, 31
	s_lshl_b64 s[38:39], s[34:35], 20
	s_add_u32 s38, s64, s38
	s_addc_u32 s39, s65, s39
	s_and_b64 s[66:67], s[4:5], exec
	s_cselect_b32 s35, s39, s69
	s_cselect_b32 s89, s38, s68
	s_ashr_i32 s21, s20, 31
	s_lshl_b64 s[66:67], s[20:21], 20
	s_add_u32 s66, s6, s66
	s_addc_u32 s67, s7, s67
	s_and_b64 s[72:73], s[4:5], exec
	s_cselect_b32 s21, s67, s71
	s_cselect_b32 s90, s66, s70
	s_add_u32 s68, s68, 0x80080
	s_addc_u32 s69, s69, 0
	s_add_u32 s91, s70, 0x100
	v_mov_b32_e32 v0, 0
	s_addc_u32 s92, s71, 0
	s_mov_b32 s93, -2
	v_mov_b32_e32 v1, v0
	v_mov_b64_e32 v[2:3], 0
	v_mov_b64_e32 v[4:5], 0
	v_mov_b64_e32 v[6:7], 0
	v_mov_b64_e32 v[8:9], 0
	v_mov_b64_e32 v[10:11], 0
	v_mov_b64_e32 v[12:13], 0
	v_mov_b64_e32 v[14:15], 0
	v_mov_b64_e32 v[16:17], 0
	v_mov_b64_e32 v[18:19], 0
	v_mov_b64_e32 v[20:21], 0
	v_mov_b64_e32 v[22:23], 0
	v_mov_b64_e32 v[24:25], 0
	v_mov_b64_e32 v[26:27], 0
	v_mov_b64_e32 v[28:29], 0
	v_mov_b64_e32 v[30:31], 0
	v_mov_b64_e32 v[32:33], 0
	v_mov_b64_e32 v[34:35], 0
	v_mov_b64_e32 v[36:37], 0
	v_mov_b64_e32 v[38:39], 0
	v_mov_b64_e32 v[40:41], 0
	v_mov_b64_e32 v[42:43], 0
	v_mov_b64_e32 v[44:45], 0
	v_mov_b64_e32 v[46:47], 0
	v_mov_b64_e32 v[48:49], 0
	v_mov_b64_e32 v[50:51], 0
	v_mov_b64_e32 v[52:53], 0
	v_mov_b64_e32 v[54:55], 0
	v_mov_b64_e32 v[56:57], 0
	v_mov_b64_e32 v[58:59], 0
	v_mov_b64_e32 v[60:61], 0
	v_mov_b64_e32 v[62:63], 0
	v_mov_b64_e32 v[64:65], 0
	v_mov_b64_e32 v[66:67], 0
	v_mov_b64_e32 v[68:69], 0
	v_mov_b64_e32 v[70:71], 0
	v_mov_b64_e32 v[72:73], 0
	v_mov_b64_e32 v[74:75], 0
	v_mov_b64_e32 v[76:77], 0
	v_mov_b64_e32 v[78:79], 0
	v_mov_b64_e32 v[80:81], 0
	v_mov_b64_e32 v[82:83], 0
	v_mov_b64_e32 v[84:85], 0
	v_mov_b64_e32 v[86:87], 0
	v_mov_b64_e32 v[88:89], 0
	v_mov_b64_e32 v[90:91], 0
	v_mov_b64_e32 v[92:93], 0
	v_mov_b64_e32 v[94:95], 0
	v_mov_b64_e32 v[96:97], 0
	v_mov_b64_e32 v[98:99], 0
	v_mov_b64_e32 v[100:101], 0
	v_mov_b64_e32 v[102:103], 0
	v_mov_b64_e32 v[104:105], 0
	v_mov_b64_e32 v[106:107], 0
	v_mov_b64_e32 v[108:109], 0
	v_mov_b64_e32 v[110:111], 0
	v_mov_b64_e32 v[112:113], 0
	v_mov_b64_e32 v[114:115], 0
	v_mov_b64_e32 v[116:117], 0
	v_mov_b64_e32 v[118:119], 0
	v_mov_b64_e32 v[120:121], 0
	v_mov_b64_e32 v[122:123], 0
	v_mov_b64_e32 v[124:125], 0
	v_mov_b64_e32 v[126:127], 0

; template <class Epi, class Sched, bool ALIGN_EPI = false, bool SP2 = false>
; __device__ __forceinline__ void gemm_phase(PG8_LAS unsigned char* lds, const Gemm g, const Sched& S, const Epi& E) {
;     ...
;         const bool has_next = S.next(ui + 1, nxt);
;         const char* nA = has_next ? (const char*)g.A + (size_t)nxt.pm * tstep : cA; const char* nB = has_next ? (const char*)g.Bt + (size_t)nxt.pn * tstep : cB;
;     ...
;         for (int a = 0; a < 2; ++a)
; #pragma unroll
;             for (int b = 0; b < 2; ++b)
; #pragma unroll
;                 for (int m = 0; m < 4; ++m)
; #pragma unroll
;                     for (int n = 0; n < 2; ++n) acc[a][b][m][n] = (f32x4){0.f, 0.f, 0.f, 0.f};
.LBB0_558:
	s_ashr_i32 s25, s24, 31
	s_lshl_b64 s[26:27], s[24:25], 20
	s_add_u32 s26, s64, s26
	s_addc_u32 s27, s65, s27
	s_and_b64 s[30:31], s[4:5], exec
	s_cselect_b32 s25, s27, s37
	s_cselect_b32 s81, s26, s36
	s_ashr_i32 s23, s22, 31
	s_lshl_b64 s[30:31], s[22:23], 20
	s_add_u32 s30, s28, s30
	s_addc_u32 s31, s29, s31
	s_and_b64 s[44:45], s[4:5], exec
	s_cselect_b32 s23, s31, s39
	s_cselect_b32 s82, s30, s38
	s_add_u32 s83, s38, 0x100
	v_mov_b32_e32 v0, 0
	s_addc_u32 s84, s39, 0
	s_mov_b32 s85, -2
	v_mov_b32_e32 v1, v0
	v_mov_b64_e32 v[2:3], 0
	v_mov_b64_e32 v[4:5], 0
	v_mov_b64_e32 v[6:7], 0
	v_mov_b64_e32 v[8:9], 0
	v_mov_b64_e32 v[10:11], 0
	v_mov_b64_e32 v[12:13], 0
	v_mov_b64_e32 v[14:15], 0
	v_mov_b64_e32 v[16:17], 0
	v_mov_b64_e32 v[18:19], 0
	v_mov_b64_e32 v[20:21], 0
	v_mov_b64_e32 v[22:23], 0
	v_mov_b64_e32 v[24:25], 0
	v_mov_b64_e32 v[26:27], 0
	v_mov_b64_e32 v[28:29], 0
	v_mov_b64_e32 v[30:31], 0
	v_mov_b64_e32 v[32:33], 0
	v_mov_b64_e32 v[34:35], 0
	v_mov_b64_e32 v[36:37], 0
	v_mov_b64_e32 v[38:39], 0
	v_mov_b64_e32 v[40:41], 0
	v_mov_b64_e32 v[42:43], 0
	v_mov_b64_e32 v[44:45], 0
	v_mov_b64_e32 v[46:47], 0
	v_mov_b64_e32 v[48:49], 0
	v_mov_b64_e32 v[50:51], 0
	v_mov_b64_e32 v[52:53], 0
	v_mov_b64_e32 v[54:55], 0
	v_mov_b64_e32 v[56:57], 0
	v_mov_b64_e32 v[58:59], 0
	v_mov_b64_e32 v[60:61], 0
	v_mov_b64_e32 v[62:63], 0
	v_mov_b64_e32 v[64:65], 0
	v_mov_b64_e32 v[66:67], 0
	v_mov_b64_e32 v[68:69], 0
	v_mov_b64_e32 v[70:71], 0
	v_mov_b64_e32 v[72:73], 0
	v_mov_b64_e32 v[74:75], 0
	v_mov_b64_e32 v[76:77], 0
	v_mov_b64_e32 v[78:79], 0
	v_mov_b64_e32 v[80:81], 0
	v_mov_b64_e32 v[82:83], 0
	v_mov_b64_e32 v[84:85], 0
	v_mov_b64_e32 v[86:87], 0
	v_mov_b64_e32 v[88:89], 0
	v_mov_b64_e32 v[90:91], 0
	v_mov_b64_e32 v[92:93], 0
	v_mov_b64_e32 v[94:95], 0
	v_mov_b64_e32 v[96:97], 0
	v_mov_b64_e32 v[98:99], 0
	v_mov_b64_e32 v[100:101], 0
	v_mov_b64_e32 v[102:103], 0
	v_mov_b64_e32 v[104:105], 0
	v_mov_b64_e32 v[106:107], 0
	v_mov_b64_e32 v[108:109], 0
	v_mov_b64_e32 v[110:111], 0
	v_mov_b64_e32 v[112:113], 0
	v_mov_b64_e32 v[114:115], 0
	v_mov_b64_e32 v[116:117], 0
	v_mov_b64_e32 v[118:119], 0
	v_mov_b64_e32 v[120:121], 0
	v_mov_b64_e32 v[122:123], 0
	v_mov_b64_e32 v[124:125], 0
	v_mov_b64_e32 v[126:127], 0

; template <class Epi, class Sched, bool ALIGN_EPI = false, bool SP2 = false>
; __device__ __forceinline__ void gemm_phase(PG8_LAS unsigned char* lds, const Gemm g, const Sched& S, const Epi& E) {
;     ...
;         const bool has_next = S.next(ui + 1, nxt);
;         const char* nA = has_next ? (const char*)g.A + (size_t)nxt.pm * tstep : cA; const char* nB = has_next ? (const char*)g.Bt + (size_t)nxt.pn * tstep : cB;
;     ...
;         for (int a = 0; a < 2; ++a)
; #pragma unroll
;             for (int b = 0; b < 2; ++b)
; #pragma unroll
;                 for (int m = 0; m < 4; ++m)
; #pragma unroll
;                     for (int n = 0; n < 2; ++n) acc[a][b][m][n] = (f32x4){0.f, 0.f, 0.f, 0.f};
.LBB0_703:
	s_ashr_i32 s89, s88, 31
	s_lshl_b64 s[12:13], s[88:89], 20
	s_add_u32 s92, s15, s12
	s_addc_u32 s93, s22, s13
	s_and_b64 s[12:13], s[36:37], exec
	s_cselect_b32 s31, s93, s9
	s_cselect_b32 s74, s92, s8
	s_ashr_i32 s39, s38, 31
	s_lshl_b64 s[12:13], s[38:39], 20
	s_add_u32 s94, s62, s12
	s_addc_u32 s95, s63, s13
	s_and_b64 s[12:13], s[36:37], exec
	s_cselect_b32 s39, s95, s11
	s_cselect_b32 s89, s94, s10
	s_add_u32 s8, s8, 0x80080
	s_addc_u32 s9, s9, 0
	s_add_u32 vcc_lo, s10, 0x100
	v_mov_b32_e32 v0, 0
	s_addc_u32 vcc_hi, s11, 0
	s_mov_b32 s34, -2
	v_mov_b32_e32 v1, v0
	v_mov_b64_e32 v[2:3], 0
	v_mov_b64_e32 v[4:5], 0
	v_mov_b64_e32 v[6:7], 0
	v_mov_b64_e32 v[8:9], 0
	v_mov_b64_e32 v[10:11], 0
	v_mov_b64_e32 v[12:13], 0
	v_mov_b64_e32 v[14:15], 0
	v_mov_b64_e32 v[16:17], 0
	v_mov_b64_e32 v[18:19], 0
	v_mov_b64_e32 v[20:21], 0
	v_mov_b64_e32 v[22:23], 0
	v_mov_b64_e32 v[24:25], 0
	v_mov_b64_e32 v[26:27], 0
	v_mov_b64_e32 v[28:29], 0
	v_mov_b64_e32 v[30:31], 0
	v_mov_b64_e32 v[32:33], 0
	v_mov_b64_e32 v[34:35], 0
	v_mov_b64_e32 v[36:37], 0
	v_mov_b64_e32 v[38:39], 0
	v_mov_b64_e32 v[40:41], 0
	v_mov_b64_e32 v[42:43], 0
	v_mov_b64_e32 v[44:45], 0
	v_mov_b64_e32 v[46:47], 0
	v_mov_b64_e32 v[48:49], 0
	v_mov_b64_e32 v[50:51], 0
	v_mov_b64_e32 v[52:53], 0
	v_mov_b64_e32 v[54:55], 0
	v_mov_b64_e32 v[56:57], 0
	v_mov_b64_e32 v[58:59], 0
	v_mov_b64_e32 v[60:61], 0
	v_mov_b64_e32 v[62:63], 0
	v_mov_b64_e32 v[64:65], 0
	v_mov_b64_e32 v[66:67], 0
	v_mov_b64_e32 v[68:69], 0
	v_mov_b64_e32 v[70:71], 0
	v_mov_b64_e32 v[72:73], 0
	v_mov_b64_e32 v[74:75], 0
	v_mov_b64_e32 v[76:77], 0
	v_mov_b64_e32 v[78:79], 0
	v_mov_b64_e32 v[80:81], 0
	v_mov_b64_e32 v[82:83], 0
	v_mov_b64_e32 v[84:85], 0
	v_mov_b64_e32 v[86:87], 0
	v_mov_b64_e32 v[88:89], 0
	v_mov_b64_e32 v[90:91], 0
	v_mov_b64_e32 v[92:93], 0
	v_mov_b64_e32 v[94:95], 0
	v_mov_b64_e32 v[96:97], 0
	v_mov_b64_e32 v[98:99], 0
	v_mov_b64_e32 v[100:101], 0
	v_mov_b64_e32 v[102:103], 0
	v_mov_b64_e32 v[104:105], 0
	v_mov_b64_e32 v[106:107], 0
	v_mov_b64_e32 v[108:109], 0
	v_mov_b64_e32 v[110:111], 0
	v_mov_b64_e32 v[112:113], 0
	v_mov_b64_e32 v[114:115], 0
	v_mov_b64_e32 v[116:117], 0
	v_mov_b64_e32 v[118:119], 0
	v_mov_b64_e32 v[120:121], 0
	v_mov_b64_e32 v[122:123], 0
	v_mov_b64_e32 v[124:125], 0
	v_mov_b64_e32 v[126:127], 0

; template <class Epi, class Sched, bool ALIGN_EPI = false, bool SP2 = false>
; __device__ __forceinline__ void gemm_phase(PG8_LAS unsigned char* lds, const Gemm g, const Sched& S, const Epi& E) {
;     ...
;         const bool has_next = S.next(ui + 1, nxt);
;         const char* nA = has_next ? (const char*)g.A + (size_t)nxt.pm * tstep : cA; const char* nB = has_next ? (const char*)g.Bt + (size_t)nxt.pn * tstep : cB;
;     ...
;         for (int a = 0; a < 2; ++a)
; #pragma unroll
;             for (int b = 0; b < 2; ++b)
; #pragma unroll
;                 for (int m = 0; m < 4; ++m)
; #pragma unroll
;                     for (int n = 0; n < 2; ++n) acc[a][b][m][n] = (f32x4){0.f, 0.f, 0.f, 0.f};
.LBB0_782:
	s_ashr_i32 s9, s8, 31
	s_lshl_b64 s[10:11], s[8:9], 22
	s_add_u32 s10, s42, s10
	s_addc_u32 s11, s43, s11
	s_and_b64 s[12:13], s[36:37], exec
	s_cselect_b32 s1, s11, s39
	s_cselect_b32 s9, s10, s38
	s_ashr_i32 s7, s6, 31
	s_lshl_b64 s[12:13], s[6:7], 22
	s_add_u32 s12, s60, s12
	s_addc_u32 s13, s61, s13
	s_and_b64 s[14:15], s[36:37], exec
	s_cselect_b32 s7, s13, s5
	s_cselect_b32 s30, s12, s4
	s_add_u32 s31, s4, 0x100
	v_mov_b32_e32 v0, 0
	s_addc_u32 s34, s5, 0
	s_mov_b32 s35, -2
	v_mov_b32_e32 v1, v0
	v_mov_b64_e32 v[2:3], 0
	v_mov_b64_e32 v[4:5], 0
	v_mov_b64_e32 v[6:7], 0
	v_mov_b64_e32 v[8:9], 0
	v_mov_b64_e32 v[10:11], 0
	v_mov_b64_e32 v[12:13], 0
	v_mov_b64_e32 v[14:15], 0
	v_mov_b64_e32 v[16:17], 0
	v_mov_b64_e32 v[18:19], 0
	v_mov_b64_e32 v[20:21], 0
	v_mov_b64_e32 v[22:23], 0
	v_mov_b64_e32 v[24:25], 0
	v_mov_b64_e32 v[26:27], 0
	v_mov_b64_e32 v[28:29], 0
	v_mov_b64_e32 v[30:31], 0
	v_mov_b64_e32 v[32:33], 0
	v_mov_b64_e32 v[34:35], 0
	v_mov_b64_e32 v[36:37], 0
	v_mov_b64_e32 v[38:39], 0
	v_mov_b64_e32 v[40:41], 0
	v_mov_b64_e32 v[42:43], 0
	v_mov_b64_e32 v[44:45], 0
	v_mov_b64_e32 v[46:47], 0
	v_mov_b64_e32 v[48:49], 0
	v_mov_b64_e32 v[50:51], 0
	v_mov_b64_e32 v[52:53], 0
	v_mov_b64_e32 v[54:55], 0
	v_mov_b64_e32 v[56:57], 0
	v_mov_b64_e32 v[58:59], 0
	v_mov_b64_e32 v[60:61], 0
	v_mov_b64_e32 v[62:63], 0
	v_mov_b64_e32 v[64:65], 0
	v_mov_b64_e32 v[66:67], 0
	v_mov_b64_e32 v[68:69], 0
	v_mov_b64_e32 v[70:71], 0
	v_mov_b64_e32 v[72:73], 0
	v_mov_b64_e32 v[74:75], 0
	v_mov_b64_e32 v[76:77], 0
	v_mov_b64_e32 v[78:79], 0
	v_mov_b64_e32 v[80:81], 0
	v_mov_b64_e32 v[82:83], 0
	v_mov_b64_e32 v[84:85], 0
	v_mov_b64_e32 v[86:87], 0
	v_mov_b64_e32 v[88:89], 0
	v_mov_b64_e32 v[90:91], 0
	v_mov_b64_e32 v[92:93], 0
	v_mov_b64_e32 v[94:95], 0
	v_mov_b64_e32 v[96:97], 0
	v_mov_b64_e32 v[98:99], 0
	v_mov_b64_e32 v[100:101], 0
	v_mov_b64_e32 v[102:103], 0
	v_mov_b64_e32 v[104:105], 0
	v_mov_b64_e32 v[106:107], 0
	v_mov_b64_e32 v[108:109], 0
	v_mov_b64_e32 v[110:111], 0
	v_mov_b64_e32 v[112:113], 0
	v_mov_b64_e32 v[114:115], 0
	v_mov_b64_e32 v[116:117], 0
	v_mov_b64_e32 v[118:119], 0
	v_mov_b64_e32 v[120:121], 0
	v_mov_b64_e32 v[122:123], 0
	v_mov_b64_e32 v[124:125], 0
	v_mov_b64_e32 v[126:127], 0
